# prep LoRA loop: weight loads software-pipelined one iteration ahead through a prefetch buffer
# baseline (speedup 1.0000x reference)
; DI void prep_phase(const Params& p, int l, char* smem, const bool dry = false) {
;     ...
;       float accw[2][8], acca[2][8];
; #pragma unroll
;       for (int ch = 0; ch < 2; ch++) {
;         const int c = tid + 256 * ch;
;         const float bw = p.w0[l * 512 + c], ba = p.a0[l * 512 + c];
; #pragma unroll
;         for (int tk = 0; tk < 8; tk++) { accw[ch][tk] = bw; acca[ch][tk] = ba; }
;       }
;       for (int i4 = 0; i4 < 16; i4++) {
;         float4 twv[8], tav[8];
; #pragma unroll
;         for (int tk = 0; tk < 8; tk++) {
;           twv[tk] = *(const float4*)(tw + tk * 64 + i4 * 4);
;           tav[tk] = *(const float4*)(ta + tk * 64 + i4 * 4);
;         }
; #pragma unroll
;         for (int ii = 0; ii < 4; ii++) {
;           const int i = i4 * 4 + ii;
; #pragma unroll
;           for (int ch = 0; ch < 2; ch++) {
;             const int c = tid + 256 * ch;
;             const float wv = w2[i * 512 + c], av = a2[i * 512 + c];
.LBB0_1175:
	s_or_b64 exec, exec, s[14:15]
	s_waitcnt lgkmcnt(0)
	s_barrier
	global_load_dword v66, v[18:19], off
	global_load_dword v50, v[18:19], off offset:1024
	global_load_dword v68, v[16:17], off
	global_load_dword v52, v[16:17], off offset:1024
	s_mov_b32 s14, 0
	s_mov_b32 s15, 0xea00
	s_waitcnt vmcnt(3)
	v_mov_b32_e32 v67, v66
	v_mov_b32_e32 v62, v66
	v_mov_b32_e32 v63, v66
	v_mov_b32_e32 v58, v66
	v_mov_b32_e32 v59, v66
	v_mov_b32_e32 v54, v66
	v_mov_b32_e32 v55, v66
	s_waitcnt vmcnt(2)
	v_mov_b32_e32 v51, v50
	v_mov_b32_e32 v46, v50
	v_mov_b32_e32 v47, v50
	v_mov_b32_e32 v42, v50
	v_mov_b32_e32 v43, v50
	v_mov_b32_e32 v38, v50
	v_mov_b32_e32 v39, v50
	s_waitcnt vmcnt(1)
	v_mov_b32_e32 v69, v68
	v_mov_b32_e32 v64, v68
	v_mov_b32_e32 v65, v68
	v_mov_b32_e32 v60, v68
	v_mov_b32_e32 v61, v68
	v_mov_b32_e32 v56, v68
	v_mov_b32_e32 v57, v68
	s_waitcnt vmcnt(0)
	v_mov_b32_e32 v53, v52
	v_mov_b32_e32 v48, v52
	v_mov_b32_e32 v49, v52
	v_mov_b32_e32 v44, v52
	v_mov_b32_e32 v45, v52
	v_mov_b32_e32 v40, v52
	v_mov_b32_e32 v41, v52
	v_add_u32_e32 v240, s14, v4
	v_lshlrev_b32_e32 v240, 2, v240
	v_add_u32_e32 v241, 0x1000, v240
	global_load_dword v224, v240, s[16:17]
	global_load_dword v225, v240, s[24:25]
	global_load_dword v226, v240, s[16:17] offset:1024
	global_load_dword v227, v240, s[24:25] offset:1024
	global_load_dword v228, v240, s[16:17] offset:2048
	global_load_dword v229, v240, s[24:25] offset:2048
	global_load_dword v230, v240, s[16:17] offset:3072
	global_load_dword v231, v240, s[24:25] offset:3072
	global_load_dword v232, v241, s[16:17]
	global_load_dword v233, v241, s[16:17] offset:2048
	global_load_dword v234, v241, s[24:25]
	global_load_dword v235, v241, s[16:17] offset:1024
	global_load_dword v236, v241, s[24:25] offset:1024
	global_load_dword v237, v241, s[24:25] offset:2048
	global_load_dword v238, v241, s[16:17] offset:3072
	global_load_dword v239, v241, s[24:25] offset:3072
.LBB0_1176:
	s_waitcnt vmcnt(0)
	v_add_u32_e32 v82, s14, v4
	v_ashrrev_i32_e32 v83, 31, v82
	v_lshlrev_b64 v[70:71], 2, v[82:83]
	v_lshl_add_u64 v[74:75], s[16:17], 0, v[70:71]
	v_lshl_add_u64 v[78:79], s[24:25], 0, v[70:71]
	v_mov_b32_e32 v104, v224
	v_mov_b32_e32 v84, v225
	v_mov_b32_e32 v72, v226
	v_mov_b32_e32 v70, v227
	v_mov_b32_e32 v124, v228
	v_mov_b32_e32 v86, v229
	v_mov_b32_e32 v76, v230
	s_nop 0
	v_mov_b32_e32 v74, v231
	v_add_u32_e32 v78, 0x400, v82
	v_ashrrev_i32_e32 v79, 31, v78
	v_lshlrev_b64 v[78:79], 2, v[78:79]
	v_lshl_add_u64 v[80:81], s[16:17], 0, v[78:79]
	v_mov_b32_e32 v126, v232
	v_add_u32_e32 v88, 0x600, v82
	v_ashrrev_i32_e32 v89, 31, v88
	v_lshlrev_b64 v[88:89], 2, v[88:89]
	v_lshl_add_u64 v[90:91], s[16:17], 0, v[88:89]
	v_mov_b32_e32 v130, v233
	v_lshl_add_u64 v[78:79], s[24:25], 0, v[78:79]
	v_mov_b32_e32 v128, v234
	v_add_u32_e32 v78, 0x500, v82
	v_ashrrev_i32_e32 v79, 31, v78
	v_lshlrev_b64 v[78:79], 2, v[78:79]
	v_lshl_add_u64 v[80:81], s[16:17], 0, v[78:79]
	v_lshl_add_u64 v[78:79], s[24:25], 0, v[78:79]
	v_lshl_add_u64 v[88:89], s[24:25], 0, v[88:89]
	v_mov_b32_e32 v71, s15
	v_mov_b32_e32 v80, v235
	v_add_u32_e32 v82, 0x700, v82
	v_mov_b32_e32 v78, v236
	v_ashrrev_i32_e32 v83, 31, v82
	v_mov_b32_e32 v132, v237
	ds_read_b128 v[88:91], v71
	ds_read_b128 v[92:95], v71 offset:256
	v_lshlrev_b64 v[82:83], 2, v[82:83]
	s_addk_i32 s14, 0x800
	v_mov_b32_e32 v252, v238
	v_mov_b32_e32 v253, v239
	s_cmpk_eq_u32 s14, 0x8000
	s_cbranch_scc1 .Lprep_nopf
	v_add_u32_e32 v240, s14, v4
	v_lshlrev_b32_e32 v240, 2, v240
	v_add_u32_e32 v241, 0x1000, v240
	global_load_dword v224, v240, s[16:17]
	global_load_dword v225, v240, s[24:25]
	global_load_dword v226, v240, s[16:17] offset:1024
	global_load_dword v227, v240, s[24:25] offset:1024
	global_load_dword v228, v240, s[16:17] offset:2048
	global_load_dword v229, v240, s[24:25] offset:2048
	global_load_dword v230, v240, s[16:17] offset:3072
	global_load_dword v231, v240, s[24:25] offset:3072
	global_load_dword v232, v241, s[16:17]
	global_load_dword v233, v241, s[16:17] offset:2048
	global_load_dword v234, v241, s[24:25]
	global_load_dword v235, v241, s[16:17] offset:1024
	global_load_dword v236, v241, s[24:25] offset:1024
	global_load_dword v237, v241, s[24:25] offset:2048
	global_load_dword v238, v241, s[16:17] offset:3072
	global_load_dword v239, v241, s[24:25] offset:3072
; DI void prep_phase(const Params& p, int l, char* smem, const bool dry = false) {
;     ...
;       for (int i4 = 0; i4 < 16; i4++) {
;         float4 twv[8], tav[8];
; #pragma unroll
;         for (int tk = 0; tk < 8; tk++) {
;           twv[tk] = *(const float4*)(tw + tk * 64 + i4 * 4);
;           tav[tk] = *(const float4*)(ta + tk * 64 + i4 * 4);
;         }
; #pragma unroll
;         for (int ii = 0; ii < 4; ii++) {
;           const int i = i4 * 4 + ii;
; #pragma unroll
;           for (int ch = 0; ch < 2; ch++) {
;             const int c = tid + 256 * ch;
;             const float wv = w2[i * 512 + c], av = a2[i * 512 + c];
; #pragma unroll
;             for (int tk = 0; tk < 8; tk++) {
;               const float x = ii == 0 ? twv[tk].x : ii == 1 ? twv[tk].y : ii == 2 ? twv[tk].z : twv[tk].w;
;               const float y = ii == 0 ? tav[tk].x : ii == 1 ? tav[tk].y : ii == 2 ? tav[tk].z : tav[tk].w;
;               accw[ch][tk] += x * wv;
;               acca[ch][tk] += y * av;
;             }
;           }
.Lprep_nopf:
	s_add_i32 s15, s15, 16
	s_waitcnt lgkmcnt(1)
	v_mov_b32_e32 v134, v88
	s_waitcnt lgkmcnt(0)
	v_mov_b32_e32 v135, v92
	v_mov_b32_e32 v92, v89
	v_mov_b32_e32 v136, v90
	v_mov_b32_e32 v137, v94
	v_mov_b32_e32 v94, v91
	ds_read_b128 v[88:91], v71 offset:2048
	ds_read_b128 v[96:99], v71 offset:2304
	s_cmpk_eq_u32 s14, 0x8000
	s_waitcnt lgkmcnt(1)
	v_mov_b32_e32 v138, v88
	s_waitcnt lgkmcnt(0)
	v_mov_b32_e32 v139, v96
	v_mov_b32_e32 v96, v89
	v_mov_b32_e32 v140, v90
	v_mov_b32_e32 v141, v98
	v_mov_b32_e32 v98, v91
	ds_read_b128 v[88:91], v71 offset:512
	ds_read_b128 v[100:103], v71 offset:768
	s_waitcnt lgkmcnt(1)
	v_mov_b32_e32 v142, v88
	s_waitcnt lgkmcnt(0)
	v_mov_b32_e32 v143, v100
	v_mov_b32_e32 v100, v89
	v_mov_b32_e32 v144, v90
	v_mov_b32_e32 v145, v102
	v_mov_b32_e32 v102, v91
	ds_read_b128 v[88:91], v71 offset:2560
	ds_read_b128 v[108:111], v71 offset:2816
	s_waitcnt lgkmcnt(1)
	v_mov_b32_e32 v146, v88
	s_waitcnt lgkmcnt(0)
	v_mov_b32_e32 v147, v108
	v_mov_b32_e32 v108, v89
	v_mov_b32_e32 v148, v90
	v_mov_b32_e32 v149, v110
	v_mov_b32_e32 v110, v91
	ds_read_b128 v[88:91], v71 offset:1024
	ds_read_b128 v[112:115], v71 offset:1280
	s_waitcnt lgkmcnt(1)
	v_mov_b32_e32 v150, v88
	s_waitcnt lgkmcnt(0)
	v_mov_b32_e32 v151, v112
	v_mov_b32_e32 v112, v89
	v_mov_b32_e32 v152, v90
	v_mov_b32_e32 v153, v114
	v_mov_b32_e32 v114, v91
	ds_read_b128 v[88:91], v71 offset:3072
	ds_read_b128 v[116:119], v71 offset:3328
	v_pk_fma_f32 v[66:67], v[138:139], v[84:85], v[66:67] op_sel_hi:[1,0,1]
	v_pk_fma_f32 v[62:63], v[146:147], v[84:85], v[62:63] op_sel_hi:[1,0,1]
	v_pk_fma_f32 v[66:67], v[96:97], v[86:87], v[66:67] op_sel_hi:[1,0,1]
	s_waitcnt lgkmcnt(1)
	v_mov_b32_e32 v154, v88
	s_waitcnt lgkmcnt(0)
	v_mov_b32_e32 v155, v116
	v_mov_b32_e32 v116, v89
	v_mov_b32_e32 v156, v90
	v_mov_b32_e32 v157, v118
	v_mov_b32_e32 v118, v91
	ds_read_b128 v[88:91], v71 offset:1536
	ds_read_b128 v[120:123], v71 offset:1792
	v_pk_fma_f32 v[68:69], v[134:135], v[104:105], v[68:69] op_sel_hi:[1,0,1]
	v_pk_fma_f32 v[64:65], v[142:143], v[104:105], v[64:65] op_sel_hi:[1,0,1]
	v_pk_fma_f32 v[60:61], v[150:151], v[104:105], v[60:61] op_sel_hi:[1,0,1]
	s_waitcnt lgkmcnt(1)
	v_mov_b32_e32 v158, v88
	s_waitcnt lgkmcnt(0)
	v_mov_b32_e32 v159, v120
	v_pk_fma_f32 v[56:57], v[158:159], v[104:105], v[56:57] op_sel_hi:[1,0,1]
	v_mov_b32_e32 v120, v89
	v_pk_fma_f32 v[68:69], v[92:93], v[124:125], v[68:69] op_sel_hi:[1,0,1]
	v_pk_fma_f32 v[64:65], v[100:101], v[124:125], v[64:65] op_sel_hi:[1,0,1]
	v_pk_fma_f32 v[60:61], v[112:113], v[124:125], v[60:61] op_sel_hi:[1,0,1]
	v_pk_fma_f32 v[56:57], v[120:121], v[124:125], v[56:57] op_sel_hi:[1,0,1]
	v_mov_b32_e32 v104, v90
	v_mov_b32_e32 v105, v122
	v_pk_fma_f32 v[68:69], v[136:137], v[126:127], v[68:69] op_sel_hi:[1,0,1]
	v_pk_fma_f32 v[64:65], v[144:145], v[126:127], v[64:65] op_sel_hi:[1,0,1]
	v_pk_fma_f32 v[60:61], v[152:153], v[126:127], v[60:61] op_sel_hi:[1,0,1]
	v_pk_fma_f32 v[56:57], v[104:105], v[126:127], v[56:57] op_sel_hi:[1,0,1]
	v_mov_b32_e32 v122, v91
	ds_read_b128 v[88:91], v71 offset:3584
	ds_read_b128 v[124:127], v71 offset:3840
	v_pk_fma_f32 v[68:69], v[94:95], v[130:131], v[68:69] op_sel_hi:[1,0,1]
	v_pk_fma_f32 v[64:65], v[102:103], v[130:131], v[64:65] op_sel_hi:[1,0,1]
	v_pk_fma_f32 v[60:61], v[114:115], v[130:131], v[60:61] op_sel_hi:[1,0,1]
	v_pk_fma_f32 v[56:57], v[122:123], v[130:131], v[56:57] op_sel_hi:[1,0,1]
	s_waitcnt lgkmcnt(1)
	v_mov_b32_e32 v130, v88
	s_waitcnt lgkmcnt(0)
	v_mov_b32_e32 v131, v124
	v_pk_fma_f32 v[58:59], v[154:155], v[84:85], v[58:59] op_sel_hi:[1,0,1]
	v_pk_fma_f32 v[54:55], v[130:131], v[84:85], v[54:55] op_sel_hi:[1,0,1]
	v_mov_b32_e32 v124, v89
	v_pk_fma_f32 v[62:63], v[108:109], v[86:87], v[62:63] op_sel_hi:[1,0,1]
	v_pk_fma_f32 v[58:59], v[116:117], v[86:87], v[58:59] op_sel_hi:[1,0,1]
	v_pk_fma_f32 v[54:55], v[124:125], v[86:87], v[54:55] op_sel_hi:[1,0,1]
	v_lshl_add_u64 v[86:87], s[16:17], 0, v[82:83]
	v_lshl_add_u64 v[82:83], s[24:25], 0, v[82:83]
	v_mov_b32_e32 v86, v252
	v_pk_fma_f32 v[52:53], v[134:135], v[72:73], v[52:53] op_sel_hi:[1,0,1]
	v_mov_b32_e32 v82, v253
	v_pk_fma_f32 v[50:51], v[138:139], v[70:71], v[50:51] op_sel_hi:[1,0,1]
	v_pk_fma_f32 v[48:49], v[142:143], v[72:73], v[48:49] op_sel_hi:[1,0,1]
	v_pk_fma_f32 v[46:47], v[146:147], v[70:71], v[46:47] op_sel_hi:[1,0,1]
	v_pk_fma_f32 v[44:45], v[150:151], v[72:73], v[44:45] op_sel_hi:[1,0,1]
	v_pk_fma_f32 v[42:43], v[154:155], v[70:71], v[42:43] op_sel_hi:[1,0,1]
	v_pk_fma_f32 v[40:41], v[158:159], v[72:73], v[40:41] op_sel_hi:[1,0,1]
	v_pk_fma_f32 v[38:39], v[130:131], v[70:71], v[38:39] op_sel_hi:[1,0,1]
	v_mov_b32_e32 v84, v90
	v_mov_b32_e32 v85, v126
	v_pk_fma_f32 v[52:53], v[92:93], v[76:77], v[52:53] op_sel_hi:[1,0,1]
	v_pk_fma_f32 v[50:51], v[96:97], v[74:75], v[50:51] op_sel_hi:[1,0,1]
	v_pk_fma_f32 v[48:49], v[100:101], v[76:77], v[48:49] op_sel_hi:[1,0,1]
	v_pk_fma_f32 v[46:47], v[108:109], v[74:75], v[46:47] op_sel_hi:[1,0,1]
	v_pk_fma_f32 v[44:45], v[112:113], v[76:77], v[44:45] op_sel_hi:[1,0,1]
	v_pk_fma_f32 v[42:43], v[116:117], v[74:75], v[42:43] op_sel_hi:[1,0,1]
	v_pk_fma_f32 v[40:41], v[120:121], v[76:77], v[40:41] op_sel_hi:[1,0,1]
	v_pk_fma_f32 v[38:39], v[124:125], v[74:75], v[38:39] op_sel_hi:[1,0,1]
	v_pk_fma_f32 v[66:67], v[140:141], v[128:129], v[66:67] op_sel_hi:[1,0,1]
	v_pk_fma_f32 v[62:63], v[148:149], v[128:129], v[62:63] op_sel_hi:[1,0,1]
	v_pk_fma_f32 v[58:59], v[156:157], v[128:129], v[58:59] op_sel_hi:[1,0,1]
	v_pk_fma_f32 v[54:55], v[84:85], v[128:129], v[54:55] op_sel_hi:[1,0,1]
	v_mov_b32_e32 v126, v91
; DI void prep_phase(const Params& p, int l, char* smem, const bool dry = false) {
;     ...
;         for (int ii = 0; ii < 4; ii++) {
;           const int i = i4 * 4 + ii;
; #pragma unroll
;           for (int ch = 0; ch < 2; ch++) {
;             const int c = tid + 256 * ch;
;             const float wv = w2[i * 512 + c], av = a2[i * 512 + c];
; #pragma unroll
;             for (int tk = 0; tk < 8; tk++) {
;               const float x = ii == 0 ? twv[tk].x : ii == 1 ? twv[tk].y : ii == 2 ? twv[tk].z : twv[tk].w;
;               const float y = ii == 0 ? tav[tk].x : ii == 1 ? tav[tk].y : ii == 2 ? tav[tk].z : tav[tk].w;
;               accw[ch][tk] += x * wv;
;               acca[ch][tk] += y * av;
;             }
;           }
;         }
;       }
;     ...
;       for (int ch = 0; ch < 2; ch++) {
;         const int c = tid + 256 * ch;
;         const int head = wave + 4 * ch;
;         const float muR = mu[c], muK = mu[512 + c], muV = mu[1024 + c];
;         const float kkc = p.k_k[l * 512 + c], kac = p.k_a[l * 512 + c], rkc = p.r_k[l * 512 + c];
; #pragma unroll
;         for (int tk = 0; tk < 8; tk++) {
;           const float* rc = rows + (tk + 1) * DSH;
;           const float* rp = rows + tk * DSH;
;           const float r = rc[c] + (rp[c] - rc[c]) * muR;
;           const float k = rc[512 + c] + (rp[512 + c] - rc[512 + c]) * muK;
;           const float v = rc[1024 + c] + (rp[1024 + c] - rc[1024 + c]) * muV;
;           const float xw = -accw[ch][tk];
;           const float sp = fmaxf(xw, 0.f) + __logf(1.f + __expf(-fabsf(xw)));
;           const float w = -sp - 0.5f;
;           const float decay = __expf(-__expf(w));
;           const float ag = __builtin_amdgcn_rcpf(1.f + __expf(-acca[ch][tk]));
;           const float kkr = k * kkc;
;           const float ss = wave_sum(kkr * kkr);
;           const float kk = kkr * fminf(__builtin_amdgcn_rsqf(ss), 1e12f);
;           const float kp = k * (1.f + (ag - 1.f) * kac);
;           const float bon = wave_sum(r * kp * rkc);
;           float* Rrow = p.R + (size_t)(tb + tk) * RS;
;           bf16_t* Rb = (bf16_t*)(Rrow + 512);
;           if (!dry) {
;             Rrow[c] = decay;
;             Rb[c] = f2bf(r);
;             Rb[512 + c] = f2bf(kp);
;             Rb[1024 + c] = f2bf(v);
;             Rb[1536 + c] = f2bf(-kk);
;             Rb[2048 + c] = f2bf(kk * ag);
	v_pk_fma_f32 v[52:53], v[136:137], v[80:81], v[52:53] op_sel_hi:[1,0,1]
	v_pk_fma_f32 v[50:51], v[140:141], v[78:79], v[50:51] op_sel_hi:[1,0,1]
	v_pk_fma_f32 v[48:49], v[144:145], v[80:81], v[48:49] op_sel_hi:[1,0,1]
	v_pk_fma_f32 v[46:47], v[148:149], v[78:79], v[46:47] op_sel_hi:[1,0,1]
	v_pk_fma_f32 v[44:45], v[152:153], v[80:81], v[44:45] op_sel_hi:[1,0,1]
	v_pk_fma_f32 v[42:43], v[156:157], v[78:79], v[42:43] op_sel_hi:[1,0,1]
	v_pk_fma_f32 v[40:41], v[104:105], v[80:81], v[40:41] op_sel_hi:[1,0,1]
	v_pk_fma_f32 v[38:39], v[84:85], v[78:79], v[38:39] op_sel_hi:[1,0,1]
	v_pk_fma_f32 v[66:67], v[98:99], v[132:133], v[66:67] op_sel_hi:[1,0,1]
	v_pk_fma_f32 v[62:63], v[110:111], v[132:133], v[62:63] op_sel_hi:[1,0,1]
	v_pk_fma_f32 v[58:59], v[118:119], v[132:133], v[58:59] op_sel_hi:[1,0,1]
	v_pk_fma_f32 v[54:55], v[126:127], v[132:133], v[54:55] op_sel_hi:[1,0,1]
	v_pk_fma_f32 v[52:53], v[94:95], v[86:87], v[52:53] op_sel_hi:[1,0,1]
	v_pk_fma_f32 v[48:49], v[102:103], v[86:87], v[48:49] op_sel_hi:[1,0,1]
	v_pk_fma_f32 v[50:51], v[98:99], v[82:83], v[50:51] op_sel_hi:[1,0,1]
	v_pk_fma_f32 v[46:47], v[110:111], v[82:83], v[46:47] op_sel_hi:[1,0,1]
	v_pk_fma_f32 v[44:45], v[114:115], v[86:87], v[44:45] op_sel_hi:[1,0,1]
	v_pk_fma_f32 v[42:43], v[118:119], v[82:83], v[42:43] op_sel_hi:[1,0,1]
	v_pk_fma_f32 v[40:41], v[122:123], v[86:87], v[40:41] op_sel_hi:[1,0,1]
	v_pk_fma_f32 v[38:39], v[126:127], v[82:83], v[38:39] op_sel_hi:[1,0,1]
	s_cbranch_scc0 .LBB0_1176
	global_load_dword v109, v[10:11], off
	global_load_dword v108, v[10:11], off offset:2048
	global_load_dword v102, v[12:13], off
	global_load_dword v105, v[20:21], off
	global_load_dword v103, v[22:23], off
	global_load_dword v104, v[24:25], off
	v_max_f32_e64 v76, -v68, -v68
	v_mul_f32_e64 v68, |v68|, s33
	v_exp_f32_e32 v68, v68
	ds_read2st64_b32 v[74:75], v107 offset0:16 offset1:26
	ds_read2st64_b32 v[70:71], v107 offset1:8
	ds_read2st64_b32 v[72:73], v107 offset0:34 offset1:42
	v_max_f32_e32 v76, 0, v76
	v_add_f32_e32 v68, 1.0, v68
	v_cmp_gt_f32_e32 vcc, s3, v68
	v_mul_f32_e32 v66, 0xbfb8aa3b, v66
	s_waitcnt lgkmcnt(0)
	v_sub_f32_e32 v71, v71, v72
	v_cndmask_b32_e64 v77, 0, 32, vcc
	v_ldexp_f32 v68, v68, v77
	v_log_f32_e32 v68, v68
	v_exp_f32_e32 v66, v66
	v_mov_b32_e32 v78, v164
	v_sub_f32_e32 v70, v70, v75
	v_mul_f32_e32 v77, 0x3f317217, v68
	v_fma_f32 v77, v68, s2, -v77
	v_fmac_f32_e32 v77, 0x3377d1cf, v68
	v_fmac_f32_e32 v77, 0x3f317217, v68
	v_cmp_lt_f32_e64 s[14:15], |v68|, s91
	v_add_f32_e32 v66, 1.0, v66
	v_rcp_f32_e32 v66, v66
	v_cndmask_b32_e64 v68, v68, v77, s[14:15]
	v_cndmask_b32_e32 v77, 0, v202, vcc
	v_sub_f32_e32 v68, v68, v77
	v_add_f32_e32 v68, v76, v68
	v_sub_f32_e32 v68, -0.5, v68
	v_mul_f32_e32 v68, 0x3fb8aa3b, v68
	v_exp_f32_e32 v68, v68
	v_mov_b32_e32 v79, v164
	v_mul_f32_e32 v68, 0xbfb8aa3b, v68
	v_exp_f32_e32 v68, v68
	s_waitcnt vmcnt(5)
	v_fma_f32 v70, v109, v70, v75
	s_waitcnt vmcnt(4)
	v_fma_f32 v71, v108, v71, v72
	s_waitcnt vmcnt(2)
	v_mul_f32_e32 v76, v105, v71
	v_mul_f32_e32 v77, v76, v76
	s_nop 1
	v_mov_b32_dpp v78, v77 quad_perm:[1,0,3,2] row_mask:0xf bank_mask:0xf
	v_fmac_f32_e32 v78, v76, v76
	s_nop 1
	v_add_f32_dpp v77, v78, v78 quad_perm:[2,3,0,1] row_mask:0xf bank_mask:0xf bound_ctrl:1
	s_nop 1
	v_add_f32_dpp v77, v77, v77 row_half_mirror row_mask:0xf bank_mask:0xf bound_ctrl:1
	s_nop 1
	v_add_f32_dpp v77, v77, v77 row_mirror row_mask:0xf bank_mask:0xf bound_ctrl:1
	s_nop 0
	v_readlane_b32 s15, v77, 16
	v_readlane_b32 s22, v77, 48
	v_readlane_b32 s14, v77, 0
	v_readlane_b32 s21, v77, 32
	v_mov_b32_e32 v77, s15
	v_mov_b32_e32 v78, s22
	v_add_f32_e32 v77, s14, v77
	v_add_f32_e32 v78, s21, v78
	v_add_f32_e32 v77, v77, v78
	v_add_f32_e32 v78, -1.0, v66
	s_waitcnt vmcnt(1)
	v_fma_f32 v78, v78, v103, 1.0
	v_mul_f32_e32 v80, v78, v71
	v_mul_f32_e32 v71, v70, v80
	s_waitcnt vmcnt(0)
	v_mul_f32_e32 v78, v104, v71
	v_rsq_f32_e32 v77, v77
	v_mad_i64_i32 v[100:101], s[22:23], s20, v203, v[34:35]
	v_mov_b32_dpp v79, v78 quad_perm:[1,0,3,2] row_mask:0xf bank_mask:0xf
	v_fmac_f32_e32 v79, v104, v71
	global_store_dword v[100:101], v68, off
	v_cvt_pk_bf16_f32 v68, v70, s0
	v_add_f32_dpp v71, v79, v79 quad_perm:[2,3,0,1] row_mask:0xf bank_mask:0xf bound_ctrl:1
	v_min_f32_e32 v77, 0x5368d4a5, v77
	v_mul_f32_e32 v76, v76, v77
	v_add_f32_dpp v71, v71, v71 row_half_mirror row_mask:0xf bank_mask:0xf bound_ctrl:1
	v_mul_f32_e32 v66, v66, v76
	s_ashr_i32 s21, s20, 31
	v_add_f32_dpp v71, v71, v71 row_mirror row_mask:0xf bank_mask:0xf bound_ctrl:1
	v_cvt_pk_bf16_f32 v66, v66, s0
	v_readlane_b32 s14, v71, 0
	v_readlane_b32 s26, v71, 16
	v_readlane_b32 s15, v71, 32
	v_readlane_b32 s27, v71, 48
	v_sub_f32_e32 v71, v74, v73
	v_fma_f32 v74, v102, v71, v73
	v_lshl_add_u64 v[70:71], v[100:101], 0, v[36:37]
	global_store_short v[70:71], v68, off offset:2048
	v_cvt_pk_bf16_f32 v68, v80, s0
	v_lshl_add_u64 v[78:79], v[70:71], 0, s[62:63]
	global_store_short v[70:71], v68, off offset:3072
	v_cvt_pk_bf16_f32 v68, v74, s0
	global_store_short v[78:79], v68, off offset:2048
	v_cvt_pk_bf16_f32 v68, -v76, s0
	v_add_co_u32_e32 v76, vcc, 0x1000, v70
	global_store_short v[78:79], v68, off offset:3072
	s_nop 0
	v_addc_co_u32_e32 v77, vcc, 0, v71, vcc
	global_store_short v[76:77], v66, off offset:2048
	s_and_saveexec_b64 s[22:23], s[10:11]
	s_cbranch_execz .LBB0_1179
	v_mov_b32_e32 v76, s26
	v_mov_b32_e32 v77, s27
	s_lshl_b64 s[28:29], s[20:21], 5
	v_pk_add_f32 v[76:77], s[14:15], v[76:77]
	s_nop 0
	v_add_f32_e32 v66, v76, v77
	v_lshl_add_u64 v[76:77], v[26:27], 0, s[28:29]
	global_store_dword v[76:77], v66, off
